# retention output cross-chunk loop: state gathers batched 8 reads per MFMA operand and double-buffered (8 counted waits instead of 32 full waits)
# speedup vs baseline: 1.0032x; 1.0032x over previous
; #define LAS __attribute__((address_space(3)))
; DI int crow(int r, int hi) { return (r & 3) + 8 * (r >> 2) + 4 * hi; }
; #define MFMA32(a, b, c) __builtin_amdgcn_mfma_f32_32x32x16_bf16((a), (b), (c), 0, 0, 0)
; DI void phase_ret_out(const Params& p, const Grp& G, int layer, LAS unsigned char* lds, int tid, int wave, int lane, bool dry) {
;     ...
;         for (int dir = 0; dir < 2; ++dir) {
;             const LAS bf16_t* S = Sl + (hh * 2 + dir) * 4096; f32x16 t[2]; t[0] = f32x16{}; t[1] = f32x16{};
; #pragma unroll
;             for (int ks = 0; ks < 4; ++ks) {
; #pragma unroll
;                 for (int cb = 0; cb < 2; ++cb) { const LAS bf16_t* sp = S + (16 * ks + 8 * hi) * 64 + 32 * cb + l31;
;                     u32x4 w; w.x = (unsigned)sp[0] | ((unsigned)sp[64] << 16); w.y = (unsigned)sp[128] | ((unsigned)sp[192] << 16); w.z = (unsigned)sp[256] | ((unsigned)sp[320] << 16); w.w = (unsigned)sp[384] | ((unsigned)sp[448] << 16);
;                     t[cb] = MFMA32(qf[ks], __builtin_bit_cast(bf16x8, w), t[cb]); }
;                 asm volatile("" ::: "memory"); }
; #pragma unroll
;             for (int r = 0; r < 16; ++r) { const int nrow = 32 * qg + crow(r, hi); const float sc = dir == 0 ? __builtin_amdgcn_exp2f(lgf * (float)(nrow + 1)) : __builtin_amdgcn_exp2f(lgb * (float)(128 - nrow));
;                 o[0][r] += t[0][r] * sc; o[1][r] += t[1][r] * sc; }
.LBB0_424:
	v_cndmask_b32_e64 v16, 0, 1, s[30:31]
	v_add_u32_e32 v227, s0, v151
	v_cmp_ne_u32_e32 vcc, 1, v16
	s_movk_i32 s0, 0x2000
	s_and_b64 vcc, exec, vcc
	ds_read_u16 v228, v227
	ds_read_u16 v232, v227 offset:128
	ds_read_u16 v229, v227 offset:256
	ds_read_u16 v233, v227 offset:384
	ds_read_u16 v230, v227 offset:512
	ds_read_u16 v234, v227 offset:640
	ds_read_u16 v231, v227 offset:768
	ds_read_u16 v235, v227 offset:896
	ds_read_u16 v236, v227 offset:64
	ds_read_u16 v240, v227 offset:192
	ds_read_u16 v237, v227 offset:320
	ds_read_u16 v241, v227 offset:448
	s_waitcnt lgkmcnt(4)
	v_lshl_or_b32 v228, v232, 16, v228
	v_lshl_or_b32 v229, v233, 16, v229
	v_lshl_or_b32 v230, v234, 16, v230
	v_lshl_or_b32 v231, v235, 16, v231
	ds_read_u16 v238, v227 offset:576
	ds_read_u16 v248, v227 offset:704
	ds_read_u16 v239, v227 offset:832
	ds_read_u16 v249, v227 offset:960
	v_mfma_f32_32x32x16_bf16 v[16:31], v[112:115], v[228:231], 0
	ds_read_u16 v228, v227 offset:2048
	ds_read_u16 v232, v227 offset:2176
	ds_read_u16 v229, v227 offset:2304
	ds_read_u16 v233, v227 offset:2432
	s_waitcnt lgkmcnt(4)
	v_lshl_or_b32 v236, v240, 16, v236
	v_lshl_or_b32 v237, v241, 16, v237
	v_lshl_or_b32 v238, v248, 16, v238
	v_lshl_or_b32 v239, v249, 16, v239
	ds_read_u16 v230, v227 offset:2560
	ds_read_u16 v234, v227 offset:2688
	ds_read_u16 v231, v227 offset:2816
	ds_read_u16 v235, v227 offset:2944
	v_mfma_f32_32x32x16_bf16 v[32:47], v[112:115], v[236:239], 0
	ds_read_u16 v236, v227 offset:2112
	ds_read_u16 v240, v227 offset:2240
	ds_read_u16 v237, v227 offset:2368
	ds_read_u16 v241, v227 offset:2496
	s_waitcnt lgkmcnt(4)
	v_lshl_or_b32 v228, v232, 16, v228
	v_lshl_or_b32 v229, v233, 16, v229
	v_lshl_or_b32 v230, v234, 16, v230
	v_lshl_or_b32 v231, v235, 16, v231
	ds_read_u16 v238, v227 offset:2624
	ds_read_u16 v248, v227 offset:2752
	ds_read_u16 v239, v227 offset:2880
	ds_read_u16 v249, v227 offset:3008
	v_mfma_f32_32x32x16_bf16 v[16:31], v[116:119], v[228:231], v[16:31]
	ds_read_u16 v228, v227 offset:4096
	ds_read_u16 v232, v227 offset:4224
	ds_read_u16 v229, v227 offset:4352
	ds_read_u16 v233, v227 offset:4480
	s_waitcnt lgkmcnt(4)
	v_lshl_or_b32 v236, v240, 16, v236
	v_lshl_or_b32 v237, v241, 16, v237
	v_lshl_or_b32 v238, v248, 16, v238
	v_lshl_or_b32 v239, v249, 16, v239
	ds_read_u16 v230, v227 offset:4608
	ds_read_u16 v234, v227 offset:4736
	ds_read_u16 v231, v227 offset:4864
	ds_read_u16 v235, v227 offset:4992
	v_mfma_f32_32x32x16_bf16 v[32:47], v[116:119], v[236:239], v[32:47]
	ds_read_u16 v236, v227 offset:4160
	ds_read_u16 v240, v227 offset:4288
	ds_read_u16 v237, v227 offset:4416
	ds_read_u16 v241, v227 offset:4544
	s_waitcnt lgkmcnt(4)
	v_lshl_or_b32 v228, v232, 16, v228
	v_lshl_or_b32 v229, v233, 16, v229
	v_lshl_or_b32 v230, v234, 16, v230
	v_lshl_or_b32 v231, v235, 16, v231
	ds_read_u16 v238, v227 offset:4672
	ds_read_u16 v248, v227 offset:4800
	ds_read_u16 v239, v227 offset:4928
	ds_read_u16 v249, v227 offset:5056
	v_mfma_f32_32x32x16_bf16 v[16:31], v[120:123], v[228:231], v[16:31]
	ds_read_u16 v228, v227 offset:6144
	ds_read_u16 v232, v227 offset:6272
	ds_read_u16 v229, v227 offset:6400
	ds_read_u16 v233, v227 offset:6528
	s_waitcnt lgkmcnt(4)
	v_lshl_or_b32 v236, v240, 16, v236
	v_lshl_or_b32 v237, v241, 16, v237
	v_lshl_or_b32 v238, v248, 16, v238
	v_lshl_or_b32 v239, v249, 16, v239
	ds_read_u16 v230, v227 offset:6656
	ds_read_u16 v234, v227 offset:6784
	ds_read_u16 v231, v227 offset:6912
	ds_read_u16 v235, v227 offset:7040
	v_mfma_f32_32x32x16_bf16 v[32:47], v[120:123], v[236:239], v[32:47]
	ds_read_u16 v236, v227 offset:6208
	ds_read_u16 v240, v227 offset:6336
	ds_read_u16 v237, v227 offset:6464
	ds_read_u16 v241, v227 offset:6592
	s_waitcnt lgkmcnt(4)
	v_lshl_or_b32 v228, v232, 16, v228
	v_lshl_or_b32 v229, v233, 16, v229
	v_lshl_or_b32 v230, v234, 16, v230
	v_lshl_or_b32 v231, v235, 16, v231
	ds_read_u16 v238, v227 offset:6720
	ds_read_u16 v248, v227 offset:6848
	ds_read_u16 v239, v227 offset:6976
	ds_read_u16 v249, v227 offset:7104
	v_mfma_f32_32x32x16_bf16 v[16:31], v[124:127], v[228:231], v[16:31]
	s_waitcnt lgkmcnt(0)
	v_lshl_or_b32 v236, v240, 16, v236
	v_lshl_or_b32 v237, v241, 16, v237
	v_lshl_or_b32 v238, v248, 16, v238
	v_lshl_or_b32 v239, v249, 16, v239
	s_nop 1
	v_mfma_f32_32x32x16_bf16 v[32:47], v[124:127], v[236:239], v[32:47]
	s_nop 4
	v_mov_b32_e32 v230, v16
	v_cndmask_b32_e64 v16, v190, v191, s[30:31]
	v_cndmask_b32_e64 v228, v188, v189, s[30:31]
	s_nop 8
	v_mov_b32_e32 v231, v32
	v_mov_b32_e32 v32, v17
	v_pk_fma_f32 v[148:149], v[16:17], v[32:33], v[148:149] op_sel_hi:[0,1,1]
	v_cndmask_b32_e64 v16, v192, v196, s[30:31]
	v_mov_b32_e32 v32, v18
	v_mov_b32_e32 v33, v34
	v_pk_fma_f32 v[2:3], v[16:17], v[32:33], v[2:3] op_sel_hi:[0,1,1]
	v_cndmask_b32_e64 v16, v197, v198, s[30:31]
	v_mov_b32_e32 v34, v19
	v_pk_fma_f32 v[146:147], v[16:17], v[34:35], v[146:147] op_sel_hi:[0,1,1]
	v_cndmask_b32_e64 v16, v199, v200, s[30:31]
	v_mov_b32_e32 v18, v20
	v_mov_b32_e32 v19, v36
	v_pk_fma_f32 v[4:5], v[16:17], v[18:19], v[4:5] op_sel_hi:[0,1,1]
	v_cndmask_b32_e64 v16, v201, v202, s[30:31]
	v_mov_b32_e32 v36, v21
	v_pk_fma_f32 v[144:145], v[16:17], v[36:37], v[144:145] op_sel_hi:[0,1,1]
	v_cndmask_b32_e64 v16, v203, v204, s[30:31]
	v_mov_b32_e32 v18, v22
	v_mov_b32_e32 v19, v38
	v_pk_fma_f32 v[6:7], v[16:17], v[18:19], v[6:7] op_sel_hi:[0,1,1]
	v_cndmask_b32_e64 v16, v205, v206, s[30:31]
	v_mov_b32_e32 v38, v23
	v_pk_fma_f32 v[142:143], v[16:17], v[38:39], v[142:143] op_sel_hi:[0,1,1]
	v_cndmask_b32_e64 v16, v207, v208, s[30:31]
	v_mov_b32_e32 v18, v24
	v_mov_b32_e32 v19, v40
	v_pk_fma_f32 v[8:9], v[16:17], v[18:19], v[8:9] op_sel_hi:[0,1,1]
	v_cndmask_b32_e64 v16, v209, v210, s[30:31]
	v_mov_b32_e32 v40, v25
	v_pk_fma_f32 v[140:141], v[16:17], v[40:41], v[140:141] op_sel_hi:[0,1,1]
	v_cndmask_b32_e64 v16, v211, v216, s[30:31]
	v_mov_b32_e32 v18, v26
	v_mov_b32_e32 v19, v42
	v_pk_fma_f32 v[10:11], v[16:17], v[18:19], v[10:11] op_sel_hi:[0,1,1]
	v_cndmask_b32_e64 v16, v217, v218, s[30:31]
	v_mov_b32_e32 v42, v27
	v_pk_fma_f32 v[138:139], v[16:17], v[42:43], v[138:139] op_sel_hi:[0,1,1]
	v_cndmask_b32_e64 v16, v219, v220, s[30:31]
	v_mov_b32_e32 v18, v28
	v_mov_b32_e32 v19, v44
	v_pk_fma_f32 v[12:13], v[16:17], v[18:19], v[12:13] op_sel_hi:[0,1,1]
	v_cndmask_b32_e64 v16, v221, v222, s[30:31]
	v_mov_b32_e32 v44, v29
	v_pk_fma_f32 v[136:137], v[16:17], v[44:45], v[136:137] op_sel_hi:[0,1,1]
	v_cndmask_b32_e64 v16, v223, v224, s[30:31]
	v_mov_b32_e32 v18, v30
	v_mov_b32_e32 v19, v46
	v_pk_fma_f32 v[14:15], v[16:17], v[18:19], v[14:15] op_sel_hi:[0,1,1]
	v_cndmask_b32_e64 v16, v225, v226, s[30:31]
	v_mov_b32_e32 v46, v31
	v_pk_fma_f32 v[0:1], v[228:229], v[230:231], v[0:1] op_sel_hi:[0,1,1]
	v_pk_fma_f32 v[134:135], v[16:17], v[46:47], v[134:135] op_sel_hi:[0,1,1]
	s_mov_b64 s[30:31], 0
	s_cbranch_vccz .LBB0_424
; #define LAS __attribute__((address_space(3)))
; DI int crow(int r, int hi) { return (r & 3) + 8 * (r >> 2) + 4 * hi; }
; DI void phase_ret_out(const Params& p, const Grp& G, int layer, LAS unsigned char* lds, int tid, int wave, int lane, bool dry) {
;     ...
;         const float g0 = p.gn[layer * 64 + l31], g1 = p.gn[layer * 64 + 32 + l31];
;         __syncthreads();
;         LAS float* stg = (LAS float*)(lds + wave * 8192);
; #pragma unroll
;         for (int r = 0; r < 16; ++r) {
;             float ss = o[0][r] * o[0][r] + o[1][r] * o[1][r]; ss = half_sum32(ss); const float ri = rsqrtf(ss * (1.0f / 64.0f) + EPSN);
;             LAS float* sp = stg + crow(r, hi) * 64 + l31; sp[0] = o[0][r] * ri * g0; sp[32] = o[1][r] * ri * g1;
;         }
	global_load_dword v19, v[132:133], off
	global_load_dword v18, v[132:133], off offset:128
	v_pk_mul_f32 v[16:17], v[0:1], v[0:1]
	v_pk_mul_f32 v[20:21], v[148:149], v[148:149]
	v_mov_b32_e32 v23, v16
	v_mov_b32_e32 v22, v20
	v_mov_b32_e32 v16, v21
	v_pk_add_f32 v[16:17], v[22:23], v[16:17]
	s_mov_b32 s0, 0x358637bd
	s_waitcnt lgkmcnt(0)
	s_barrier
	s_nop 1
	v_add_f32_dpp v16, v16, v16 quad_perm:[1,0,3,2] row_mask:0xf bank_mask:0xf
	v_add_f32_dpp v17, v17, v17 quad_perm:[1,0,3,2] row_mask:0xf bank_mask:0xf
	s_waitcnt lgkmcnt(0)
	s_nop 1
	v_add_f32_dpp v16, v16, v16 quad_perm:[2,3,0,1] row_mask:0xf bank_mask:0xf
	v_add_f32_dpp v17, v17, v17 quad_perm:[2,3,0,1] row_mask:0xf bank_mask:0xf
	s_waitcnt lgkmcnt(0)
	s_nop 1
	v_add_f32_dpp v16, v16, v16 row_half_mirror row_mask:0xf bank_mask:0xf
	v_add_f32_dpp v17, v17, v17 row_half_mirror row_mask:0xf bank_mask:0xf
	s_waitcnt lgkmcnt(0)
	s_nop 1
	v_add_f32_dpp v16, v16, v16 row_ror:8 row_mask:0xf bank_mask:0xf
	v_add_f32_dpp v17, v17, v17 row_ror:8 row_mask:0xf bank_mask:0xf
	ds_bpermute_b32 v21, v215, v17
	ds_bpermute_b32 v20, v215, v16
	s_waitcnt lgkmcnt(0)
	v_pk_add_f32 v[20:21], v[16:17], v[20:21]
	v_mov_b64_e32 v[16:17], s[0:1]
	s_mov_b32 s0, 0x3c800000
	v_pk_fma_f32 v[20:21], v[20:21], s[0:1], v[16:17] op_sel_hi:[1,0,0]
	s_nop 0
	v_mul_f32_e32 v22, 0x4b800000, v21
	v_cmp_gt_f32_e64 s[38:39], s90, v21
	v_cmp_gt_f32_e32 vcc, s90, v20
	s_nop 0
	v_cndmask_b32_e64 v21, v21, v22, s[38:39]
	v_rsq_f32_e32 v21, v21
	s_nop 0
	v_mul_f32_e32 v22, 0x45800000, v21
	v_cndmask_b32_e64 v21, v21, v22, s[38:39]
	v_mul_f32_e32 v0, v0, v21
	v_mul_f32_e32 v1, v1, v21
	s_waitcnt vmcnt(1)
	v_mul_f32_e32 v0, v19, v0
	s_waitcnt vmcnt(0)
	v_mul_f32_e32 v1, v18, v1
	ds_write2_b32 v152, v0, v1 offset1:32
	v_mul_f32_e32 v0, 0x4b800000, v20
	v_cndmask_b32_e32 v0, v20, v0, vcc
	v_rsq_f32_e32 v0, v0
	v_pk_mul_f32 v[20:21], v[146:147], v[146:147]
	v_mul_f32_e32 v1, 0x45800000, v0
	v_cndmask_b32_e32 v0, v0, v1, vcc
	v_mul_f32_e32 v1, v148, v0
	v_mul_f32_e32 v0, v149, v0
	v_mul_f32_e32 v1, v19, v1
	v_mul_f32_e32 v0, v18, v0
	ds_write2_b32 v152, v1, v0 offset0:64 offset1:96
	v_pk_mul_f32 v[0:1], v[2:3], v[2:3]
	v_mov_b32_e32 v22, v20
	v_mov_b32_e32 v23, v0
	v_mov_b32_e32 v0, v21
	v_pk_add_f32 v[0:1], v[22:23], v[0:1]
	s_waitcnt lgkmcnt(0)
	s_nop 1
	v_add_f32_dpp v0, v0, v0 quad_perm:[1,0,3,2] row_mask:0xf bank_mask:0xf
	v_add_f32_dpp v1, v1, v1 quad_perm:[1,0,3,2] row_mask:0xf bank_mask:0xf
	s_waitcnt lgkmcnt(0)
	s_nop 1
	v_add_f32_dpp v0, v0, v0 quad_perm:[2,3,0,1] row_mask:0xf bank_mask:0xf
	v_add_f32_dpp v1, v1, v1 quad_perm:[2,3,0,1] row_mask:0xf bank_mask:0xf
	s_waitcnt lgkmcnt(0)
	s_nop 1
	v_add_f32_dpp v0, v0, v0 row_half_mirror row_mask:0xf bank_mask:0xf
	v_add_f32_dpp v1, v1, v1 row_half_mirror row_mask:0xf bank_mask:0xf
	s_waitcnt lgkmcnt(0)
	s_nop 1
	v_add_f32_dpp v0, v0, v0 row_ror:8 row_mask:0xf bank_mask:0xf
	v_add_f32_dpp v1, v1, v1 row_ror:8 row_mask:0xf bank_mask:0xf
	ds_bpermute_b32 v21, v215, v1
	ds_bpermute_b32 v20, v215, v0
	s_waitcnt lgkmcnt(0)
	v_pk_add_f32 v[0:1], v[0:1], v[20:21]
	s_nop 0
	v_pk_fma_f32 v[0:1], v[0:1], s[0:1], v[16:17] op_sel_hi:[1,0,0]
	s_nop 0
	v_mul_f32_e32 v20, 0x4b800000, v1
	v_cmp_gt_f32_e64 s[38:39], s90, v1
	v_cmp_gt_f32_e32 vcc, s90, v0
	s_nop 0
	v_cndmask_b32_e64 v1, v1, v20, s[38:39]
	v_rsq_f32_e32 v1, v1
	s_nop 0
	v_mul_f32_e32 v20, 0x45800000, v1
	v_cndmask_b32_e64 v1, v1, v20, s[38:39]
	v_mul_f32_e32 v2, v2, v1
	v_mul_f32_e32 v1, v3, v1
	v_mul_f32_e32 v2, v19, v2
	v_mul_f32_e32 v1, v18, v1
	ds_write2_b32 v152, v2, v1 offset0:128 offset1:160
	v_mul_f32_e32 v1, 0x4b800000, v0
	v_cndmask_b32_e32 v0, v0, v1, vcc
	v_rsq_f32_e32 v0, v0
	v_pk_mul_f32 v[2:3], v[144:145], v[144:145]
	v_mul_f32_e32 v1, 0x45800000, v0
	v_cndmask_b32_e32 v0, v0, v1, vcc
	v_mul_f32_e32 v1, v146, v0
	v_mul_f32_e32 v0, v147, v0
	v_mul_f32_e32 v1, v19, v1
	v_mul_f32_e32 v0, v18, v0
	ds_write2_b32 v152, v1, v0 offset0:192 offset1:224
	v_pk_mul_f32 v[0:1], v[4:5], v[4:5]
	v_mov_b32_e32 v20, v2
	v_mov_b32_e32 v21, v0
	v_mov_b32_e32 v0, v3
	v_pk_add_f32 v[0:1], v[20:21], v[0:1]
	v_add_u32_e32 v20, 0x800, v152
	s_waitcnt lgkmcnt(0)
	s_nop 1
	v_add_f32_dpp v0, v0, v0 quad_perm:[1,0,3,2] row_mask:0xf bank_mask:0xf
	v_add_f32_dpp v1, v1, v1 quad_perm:[1,0,3,2] row_mask:0xf bank_mask:0xf
	s_waitcnt lgkmcnt(0)
	s_nop 1
	v_add_f32_dpp v0, v0, v0 quad_perm:[2,3,0,1] row_mask:0xf bank_mask:0xf
	v_add_f32_dpp v1, v1, v1 quad_perm:[2,3,0,1] row_mask:0xf bank_mask:0xf
	s_waitcnt lgkmcnt(0)
	s_nop 1
	v_add_f32_dpp v0, v0, v0 row_half_mirror row_mask:0xf bank_mask:0xf
	v_add_f32_dpp v1, v1, v1 row_half_mirror row_mask:0xf bank_mask:0xf
	s_waitcnt lgkmcnt(0)
	s_nop 1
	v_add_f32_dpp v0, v0, v0 row_ror:8 row_mask:0xf bank_mask:0xf
	v_add_f32_dpp v1, v1, v1 row_ror:8 row_mask:0xf bank_mask:0xf
	ds_bpermute_b32 v3, v215, v1
	ds_bpermute_b32 v2, v215, v0
	s_waitcnt lgkmcnt(0)
	v_pk_add_f32 v[0:1], v[0:1], v[2:3]
	s_nop 0
	v_pk_fma_f32 v[0:1], v[0:1], s[0:1], v[16:17] op_sel_hi:[1,0,0]
	s_nop 0
	v_mul_f32_e32 v2, 0x4b800000, v1
	v_cmp_gt_f32_e64 s[38:39], s90, v1
	v_cmp_gt_f32_e32 vcc, s90, v0
	s_nop 0
	v_cndmask_b32_e64 v1, v1, v2, s[38:39]
	v_rsq_f32_e32 v1, v1
	s_nop 0
	v_mul_f32_e32 v2, 0x45800000, v1
	v_cndmask_b32_e64 v1, v1, v2, s[38:39]
	v_mul_f32_e32 v2, v4, v1
	v_mul_f32_e32 v1, v5, v1
	v_mul_f32_e32 v2, v19, v2
	v_mul_f32_e32 v1, v18, v1
	ds_write2_b32 v20, v2, v1 offset1:32
	v_mul_f32_e32 v1, 0x4b800000, v0
	v_cndmask_b32_e32 v0, v0, v1, vcc
	v_rsq_f32_e32 v0, v0
	v_pk_mul_f32 v[2:3], v[142:143], v[142:143]
	v_mul_f32_e32 v1, 0x45800000, v0
	v_cndmask_b32_e32 v0, v0, v1, vcc
	v_mul_f32_e32 v1, v144, v0
	v_mul_f32_e32 v0, v145, v0
	v_mul_f32_e32 v1, v19, v1
	v_mul_f32_e32 v0, v18, v0
	ds_write2_b32 v20, v1, v0 offset0:64 offset1:96
	v_pk_mul_f32 v[0:1], v[6:7], v[6:7]
	v_mov_b32_e32 v4, v2
	v_mov_b32_e32 v5, v0
	v_mov_b32_e32 v0, v3
	v_pk_add_f32 v[0:1], v[4:5], v[0:1]
	s_waitcnt lgkmcnt(0)
; #define LAS __attribute__((address_space(3)))
; DI int crow(int r, int hi) { return (r & 3) + 8 * (r >> 2) + 4 * hi; }
; DI void phase_ret_out(const Params& p, const Grp& G, int layer, LAS unsigned char* lds, int tid, int wave, int lane, bool dry) {
;     ...
; #pragma unroll
;         for (int r = 0; r < 16; ++r) {
;             float ss = o[0][r] * o[0][r] + o[1][r] * o[1][r]; ss = half_sum32(ss); const float ri = rsqrtf(ss * (1.0f / 64.0f) + EPSN);
;             LAS float* sp = stg + crow(r, hi) * 64 + l31; sp[0] = o[0][r] * ri * g0; sp[32] = o[1][r] * ri * g1;
;         }
	s_nop 1
	v_add_f32_dpp v0, v0, v0 quad_perm:[1,0,3,2] row_mask:0xf bank_mask:0xf
	v_add_f32_dpp v1, v1, v1 quad_perm:[1,0,3,2] row_mask:0xf bank_mask:0xf
	s_waitcnt lgkmcnt(0)
	s_nop 1
	v_add_f32_dpp v0, v0, v0 quad_perm:[2,3,0,1] row_mask:0xf bank_mask:0xf
	v_add_f32_dpp v1, v1, v1 quad_perm:[2,3,0,1] row_mask:0xf bank_mask:0xf
	s_waitcnt lgkmcnt(0)
	s_nop 1
	v_add_f32_dpp v0, v0, v0 row_half_mirror row_mask:0xf bank_mask:0xf
	v_add_f32_dpp v1, v1, v1 row_half_mirror row_mask:0xf bank_mask:0xf
	s_waitcnt lgkmcnt(0)
	s_nop 1
	v_add_f32_dpp v0, v0, v0 row_ror:8 row_mask:0xf bank_mask:0xf
	v_add_f32_dpp v1, v1, v1 row_ror:8 row_mask:0xf bank_mask:0xf
	ds_bpermute_b32 v3, v215, v1
	ds_bpermute_b32 v2, v215, v0
	s_waitcnt lgkmcnt(0)
	v_pk_add_f32 v[0:1], v[0:1], v[2:3]
	s_nop 0
	v_pk_fma_f32 v[0:1], v[0:1], s[0:1], v[16:17] op_sel_hi:[1,0,0]
	s_nop 0
	v_mul_f32_e32 v2, 0x4b800000, v1
	v_cmp_gt_f32_e64 s[38:39], s90, v1
	v_cmp_gt_f32_e32 vcc, s90, v0
	s_nop 0
	v_cndmask_b32_e64 v1, v1, v2, s[38:39]
	v_rsq_f32_e32 v1, v1
	s_nop 0
	v_mul_f32_e32 v2, 0x45800000, v1
	v_cndmask_b32_e64 v1, v1, v2, s[38:39]
	v_mul_f32_e32 v2, v6, v1
	v_mul_f32_e32 v1, v7, v1
	v_mul_f32_e32 v2, v19, v2
	v_mul_f32_e32 v1, v18, v1
	ds_write2_b32 v20, v2, v1 offset0:128 offset1:160
	v_mul_f32_e32 v1, 0x4b800000, v0
	v_cndmask_b32_e32 v0, v0, v1, vcc
	v_rsq_f32_e32 v0, v0
	v_pk_mul_f32 v[2:3], v[140:141], v[140:141]
	v_add_u32_e32 v6, 0x1000, v152
	v_mov_b32_e32 v4, v2
	v_mul_f32_e32 v1, 0x45800000, v0
	v_cndmask_b32_e32 v0, v0, v1, vcc
	v_mul_f32_e32 v1, v142, v0
	v_mul_f32_e32 v0, v143, v0
	v_mul_f32_e32 v1, v19, v1
	v_mul_f32_e32 v0, v18, v0
	ds_write2_b32 v20, v1, v0 offset0:192 offset1:224
	v_pk_mul_f32 v[0:1], v[8:9], v[8:9]
	s_nop 0
	v_mov_b32_e32 v5, v0
	v_mov_b32_e32 v0, v3
	v_pk_add_f32 v[0:1], v[4:5], v[0:1]
	s_waitcnt lgkmcnt(0)
	s_nop 1
	v_add_f32_dpp v0, v0, v0 quad_perm:[1,0,3,2] row_mask:0xf bank_mask:0xf
	v_add_f32_dpp v1, v1, v1 quad_perm:[1,0,3,2] row_mask:0xf bank_mask:0xf
	s_waitcnt lgkmcnt(0)
	s_nop 1
	v_add_f32_dpp v0, v0, v0 quad_perm:[2,3,0,1] row_mask:0xf bank_mask:0xf
	v_add_f32_dpp v1, v1, v1 quad_perm:[2,3,0,1] row_mask:0xf bank_mask:0xf
	s_waitcnt lgkmcnt(0)
	s_nop 1
	v_add_f32_dpp v0, v0, v0 row_half_mirror row_mask:0xf bank_mask:0xf
	v_add_f32_dpp v1, v1, v1 row_half_mirror row_mask:0xf bank_mask:0xf
	s_waitcnt lgkmcnt(0)
	s_nop 1
	v_add_f32_dpp v0, v0, v0 row_ror:8 row_mask:0xf bank_mask:0xf
	v_add_f32_dpp v1, v1, v1 row_ror:8 row_mask:0xf bank_mask:0xf
	ds_bpermute_b32 v3, v215, v1
	ds_bpermute_b32 v2, v215, v0
	s_waitcnt lgkmcnt(0)
	v_pk_add_f32 v[0:1], v[0:1], v[2:3]
	s_nop 0
	v_pk_fma_f32 v[0:1], v[0:1], s[0:1], v[16:17] op_sel_hi:[1,0,0]
	s_nop 0
	v_mul_f32_e32 v2, 0x4b800000, v1
	v_cmp_gt_f32_e64 s[38:39], s90, v1
	v_cmp_gt_f32_e32 vcc, s90, v0
	s_nop 0
	v_cndmask_b32_e64 v1, v1, v2, s[38:39]
	v_rsq_f32_e32 v1, v1
	s_nop 0
	v_mul_f32_e32 v2, 0x45800000, v1
	v_cndmask_b32_e64 v1, v1, v2, s[38:39]
	v_mul_f32_e32 v2, v8, v1
	v_mul_f32_e32 v1, v9, v1
	v_mul_f32_e32 v2, v19, v2
	v_mul_f32_e32 v1, v18, v1
	ds_write2_b32 v6, v2, v1 offset1:32
	v_mul_f32_e32 v1, 0x4b800000, v0
	v_cndmask_b32_e32 v0, v0, v1, vcc
	v_rsq_f32_e32 v0, v0
	v_pk_mul_f32 v[2:3], v[138:139], v[138:139]
	v_mul_f32_e32 v1, 0x45800000, v0
	v_cndmask_b32_e32 v0, v0, v1, vcc
	v_mul_f32_e32 v1, v140, v0
	v_mul_f32_e32 v0, v141, v0
	v_mul_f32_e32 v1, v19, v1
	v_mul_f32_e32 v0, v18, v0
	ds_write2_b32 v6, v1, v0 offset0:64 offset1:96
	v_pk_mul_f32 v[0:1], v[10:11], v[10:11]
	v_mov_b32_e32 v4, v2
	v_mov_b32_e32 v5, v0
	v_mov_b32_e32 v0, v3
	v_pk_add_f32 v[0:1], v[4:5], v[0:1]
	s_waitcnt lgkmcnt(0)
	s_nop 1
	v_add_f32_dpp v0, v0, v0 quad_perm:[1,0,3,2] row_mask:0xf bank_mask:0xf
	v_add_f32_dpp v1, v1, v1 quad_perm:[1,0,3,2] row_mask:0xf bank_mask:0xf
	s_waitcnt lgkmcnt(0)
	s_nop 1
	v_add_f32_dpp v0, v0, v0 quad_perm:[2,3,0,1] row_mask:0xf bank_mask:0xf
	v_add_f32_dpp v1, v1, v1 quad_perm:[2,3,0,1] row_mask:0xf bank_mask:0xf
	s_waitcnt lgkmcnt(0)
	s_nop 1
	v_add_f32_dpp v0, v0, v0 row_half_mirror row_mask:0xf bank_mask:0xf
	v_add_f32_dpp v1, v1, v1 row_half_mirror row_mask:0xf bank_mask:0xf
	s_waitcnt lgkmcnt(0)
	s_nop 1
	v_add_f32_dpp v0, v0, v0 row_ror:8 row_mask:0xf bank_mask:0xf
	v_add_f32_dpp v1, v1, v1 row_ror:8 row_mask:0xf bank_mask:0xf
	ds_bpermute_b32 v3, v215, v1
	ds_bpermute_b32 v2, v215, v0
	s_waitcnt lgkmcnt(0)
	v_pk_add_f32 v[0:1], v[0:1], v[2:3]
	s_nop 0
	v_pk_fma_f32 v[0:1], v[0:1], s[0:1], v[16:17] op_sel_hi:[1,0,0]
	s_nop 0
	v_mul_f32_e32 v2, 0x4b800000, v1
	v_cmp_gt_f32_e64 s[38:39], s90, v1
	v_cmp_gt_f32_e32 vcc, s90, v0
	s_nop 0
	v_cndmask_b32_e64 v1, v1, v2, s[38:39]
	v_rsq_f32_e32 v1, v1
	s_nop 0
	v_mul_f32_e32 v2, 0x45800000, v1
	v_cndmask_b32_e64 v1, v1, v2, s[38:39]
	v_mul_f32_e32 v2, v10, v1
	v_mul_f32_e32 v1, v11, v1
	v_mul_f32_e32 v2, v19, v2
	v_mul_f32_e32 v1, v18, v1
	ds_write2_b32 v6, v2, v1 offset0:128 offset1:160
	v_mul_f32_e32 v1, 0x4b800000, v0
	v_cndmask_b32_e32 v0, v0, v1, vcc
	v_rsq_f32_e32 v0, v0
	v_pk_mul_f32 v[2:3], v[136:137], v[136:137]
	v_mul_f32_e32 v1, 0x45800000, v0
	v_cndmask_b32_e32 v0, v0, v1, vcc
	v_mul_f32_e32 v1, v138, v0
	v_mul_f32_e32 v0, v139, v0
	v_mul_f32_e32 v1, v19, v1
	v_mul_f32_e32 v0, v18, v0
	ds_write2_b32 v6, v1, v0 offset0:192 offset1:224
	v_pk_mul_f32 v[0:1], v[12:13], v[12:13]
	v_mov_b32_e32 v4, v2
	v_mov_b32_e32 v5, v0
	v_mov_b32_e32 v0, v3
	v_pk_add_f32 v[0:1], v[4:5], v[0:1]
	v_add_u32_e32 v6, 0x1800, v152
	s_waitcnt lgkmcnt(0)
	s_nop 1
	v_add_f32_dpp v0, v0, v0 quad_perm:[1,0,3,2] row_mask:0xf bank_mask:0xf
	v_add_f32_dpp v1, v1, v1 quad_perm:[1,0,3,2] row_mask:0xf bank_mask:0xf
	s_waitcnt lgkmcnt(0)
; #define LAS __attribute__((address_space(3)))
; DI unsigned pk2(float lo, float hi) { typedef float f2 __attribute__((ext_vector_type(2))); typedef __bf16 b2 __attribute__((ext_vector_type(2))); f2 v = {lo, hi}; b2 b = __builtin_convertvector(v, b2); return __builtin_bit_cast(unsigned, b); }
; DI float bf_lo(unsigned w) { return __uint_as_float(w << 16); }
; DI float bf_hi(unsigned w) { return __uint_as_float(w & 0xffff0000u); }
; DI int crow(int r, int hi) { return (r & 3) + 8 * (r >> 2) + 4 * hi; }
; DI void phase_ret_out(const Params& p, const Grp& G, int layer, LAS unsigned char* lds, int tid, int wave, int lane, bool dry) {
;     ...
;         for (int r = 0; r < 16; ++r) {
;             float ss = o[0][r] * o[0][r] + o[1][r] * o[1][r]; ss = half_sum32(ss); const float ri = rsqrtf(ss * (1.0f / 64.0f) + EPSN);
;             LAS float* sp = stg + crow(r, hi) * 64 + l31; sp[0] = o[0][r] * ri * g0; sp[32] = o[1][r] * ri * g1;
;         }
;         asm volatile("s_waitcnt lgkmcnt(0)" ::: "memory");
;         { int lv = lane; asm volatile("" : "+v"(lv));
;           bf16_t* ob = (dry ? (bf16_t*)(p.ws + OFF_DUMMY) : mix + row0 * MIXW) + (size_t)(32 * qg) * MIXW + 512 + head * 64; const bf16_t* gb = rest + (row0 + 32 * qg) * RESTW + R_RG + head * 64;
; #pragma unroll
;           for (int i = 0; i < 4; ++i) { const int q = lv + 64 * i, row = q >> 3, ch = q & 7;
;             const f32x4 a0 = *(const LAS f32x4*)(stg + row * 64 + ch * 8), a1 = *(const LAS f32x4*)(stg + row * 64 + ch * 8 + 4);
;             const u32x4 gw = gwv[i];
;             float gv[8] = {bf_lo(gw.x), bf_hi(gw.x), bf_lo(gw.y), bf_hi(gw.y), bf_lo(gw.z), bf_hi(gw.z), bf_lo(gw.w), bf_hi(gw.w)}; float ov[8];
; #pragma unroll
;             for (int e = 0; e < 8; ++e) ov[e] = (e < 4 ? a0[e & 3] : a1[e & 3]) * (gv[e] * __builtin_amdgcn_rcpf(1.f + __expf(-gv[e])));
;             u32x4 w; w.x = pk2(ov[0], ov[1]); w.y = pk2(ov[2], ov[3]); w.z = pk2(ov[4], ov[5]); w.w = pk2(ov[6], ov[7]);
;             *(u32x4*)(ob + (size_t)row * MIXW + ch * 8) = w; } }
	s_nop 1
	v_add_f32_dpp v0, v0, v0 quad_perm:[2,3,0,1] row_mask:0xf bank_mask:0xf
	v_add_f32_dpp v1, v1, v1 quad_perm:[2,3,0,1] row_mask:0xf bank_mask:0xf
	s_waitcnt lgkmcnt(0)
	s_nop 1
	v_add_f32_dpp v0, v0, v0 row_half_mirror row_mask:0xf bank_mask:0xf
	v_add_f32_dpp v1, v1, v1 row_half_mirror row_mask:0xf bank_mask:0xf
	s_waitcnt lgkmcnt(0)
	s_nop 1
	v_add_f32_dpp v0, v0, v0 row_ror:8 row_mask:0xf bank_mask:0xf
	v_add_f32_dpp v1, v1, v1 row_ror:8 row_mask:0xf bank_mask:0xf
	ds_bpermute_b32 v3, v215, v1
	ds_bpermute_b32 v2, v215, v0
	s_waitcnt lgkmcnt(0)
	v_pk_add_f32 v[0:1], v[0:1], v[2:3]
	s_nop 0
	v_pk_fma_f32 v[0:1], v[0:1], s[0:1], v[16:17] op_sel_hi:[1,0,0]
	s_nop 0
	v_mul_f32_e32 v2, 0x4b800000, v1
	v_cmp_gt_f32_e64 s[38:39], s90, v1
	v_cmp_gt_f32_e32 vcc, s90, v0
	s_nop 0
	v_cndmask_b32_e64 v1, v1, v2, s[38:39]
	v_rsq_f32_e32 v1, v1
	s_nop 0
	v_mul_f32_e32 v2, 0x45800000, v1
	v_cndmask_b32_e64 v1, v1, v2, s[38:39]
	v_mul_f32_e32 v2, v12, v1
	v_mul_f32_e32 v1, v13, v1
	v_mul_f32_e32 v2, v19, v2
	v_mul_f32_e32 v1, v18, v1
	ds_write2_b32 v6, v2, v1 offset1:32
	v_mul_f32_e32 v1, 0x4b800000, v0
	v_cndmask_b32_e32 v0, v0, v1, vcc
	v_rsq_f32_e32 v0, v0
	v_pk_mul_f32 v[2:3], v[134:135], v[134:135]
	v_mul_f32_e32 v1, 0x45800000, v0
	v_cndmask_b32_e32 v0, v0, v1, vcc
	v_mul_f32_e32 v1, v136, v0
	v_mul_f32_e32 v0, v137, v0
	v_mul_f32_e32 v1, v19, v1
	v_mul_f32_e32 v0, v18, v0
	ds_write2_b32 v6, v1, v0 offset0:64 offset1:96
	v_pk_mul_f32 v[0:1], v[14:15], v[14:15]
	v_mov_b32_e32 v4, v2
	v_mov_b32_e32 v5, v0
	v_mov_b32_e32 v0, v3
	v_pk_add_f32 v[0:1], v[4:5], v[0:1]
	s_waitcnt lgkmcnt(0)
	s_nop 1
	v_add_f32_dpp v0, v0, v0 quad_perm:[1,0,3,2] row_mask:0xf bank_mask:0xf
	v_add_f32_dpp v1, v1, v1 quad_perm:[1,0,3,2] row_mask:0xf bank_mask:0xf
	s_waitcnt lgkmcnt(0)
	s_nop 1
	v_add_f32_dpp v0, v0, v0 quad_perm:[2,3,0,1] row_mask:0xf bank_mask:0xf
	v_add_f32_dpp v1, v1, v1 quad_perm:[2,3,0,1] row_mask:0xf bank_mask:0xf
	s_waitcnt lgkmcnt(0)
	s_nop 1
	v_add_f32_dpp v0, v0, v0 row_half_mirror row_mask:0xf bank_mask:0xf
	v_add_f32_dpp v1, v1, v1 row_half_mirror row_mask:0xf bank_mask:0xf
	s_waitcnt lgkmcnt(0)
	s_nop 1
	v_add_f32_dpp v0, v0, v0 row_ror:8 row_mask:0xf bank_mask:0xf
	v_add_f32_dpp v1, v1, v1 row_ror:8 row_mask:0xf bank_mask:0xf
	ds_bpermute_b32 v3, v215, v1
	ds_bpermute_b32 v2, v215, v0
	s_waitcnt lgkmcnt(0)
	v_pk_add_f32 v[0:1], v[0:1], v[2:3]
	s_nop 0
	v_pk_fma_f32 v[0:1], v[0:1], s[0:1], v[16:17] op_sel_hi:[1,0,0]
	s_lshl_b64 s[0:1], s[42:43], 11
	v_mul_f32_e32 v2, 0x4b800000, v1
	v_cmp_gt_f32_e64 s[38:39], s90, v1
	v_cmp_gt_f32_e32 vcc, s90, v0
	s_add_u32 s0, s45, s0
	v_cndmask_b32_e64 v1, v1, v2, s[38:39]
	v_rsq_f32_e32 v1, v1
	s_addc_u32 s1, s52, s1
	s_lshl_b32 s4, s4, 1
	s_add_u32 s0, s0, s4
	v_mul_f32_e32 v2, 0x45800000, v1
	v_cndmask_b32_e64 v1, v1, v2, s[38:39]
	v_mul_f32_e32 v2, v14, v1
	v_mul_f32_e32 v1, v15, v1
	v_mul_f32_e32 v2, v19, v2
	v_mul_f32_e32 v1, v18, v1
	ds_write2_b32 v6, v2, v1 offset0:128 offset1:160
	v_mul_f32_e32 v1, 0x4b800000, v0
	v_cndmask_b32_e32 v0, v0, v1, vcc
	v_lshlrev_b32_e32 v14, 16, v108
	v_rsq_f32_e32 v0, v0
	v_mul_f32_e32 v13, 0xbfb8aa3b, v14
	v_exp_f32_e32 v13, v13
	v_and_b32_e32 v15, 0xffff0000, v108
	v_mul_f32_e32 v1, 0x45800000, v0
	v_cndmask_b32_e32 v0, v0, v1, vcc
	v_add_f32_e32 v13, 1.0, v13
	v_mul_f32_e32 v1, v134, v0
	v_mul_f32_e32 v0, v135, v0
	v_rcp_f32_e32 v16, v13
	v_mul_f32_e32 v13, 0xbfb8aa3b, v15
	v_mul_f32_e32 v1, v19, v1
	v_mul_f32_e32 v0, v18, v0
	v_exp_f32_e32 v13, v13
	ds_write2_b32 v6, v1, v0 offset0:192 offset1:224
	v_mov_b32_e32 v2, v129
	s_waitcnt lgkmcnt(0)
	v_add_f32_e32 v13, 1.0, v13
	v_lshlrev_b32_e32 v0, 3, v2
	v_and_b32_e32 v0, 56, v0
	v_lshl_add_u32 v3, v0, 2, s60
	v_ashrrev_i32_e32 v12, 3, v2
	v_lshl_add_u32 v8, v12, 8, v3
	v_rcp_f32_e32 v17, v13
	ds_read_b128 v[4:7], v8
	ds_read_b128 v[8:11], v8 offset:16
	s_addc_u32 s1, s1, 0
	v_lshlrev_b32_e32 v192, 1, v0
	v_pk_mul_f32 v[14:15], v[16:17], v[14:15]
	v_lshl_add_u64 v[0:1], s[0:1], 0, v[192:193]
	s_waitcnt lgkmcnt(1)
	v_pk_mul_f32 v[4:5], v[14:15], v[4:5]
	v_lshlrev_b32_e32 v14, 16, v109
	v_mul_f32_e32 v13, 0xbfb8aa3b, v14
	v_exp_f32_e32 v13, v13
	v_and_b32_e32 v15, 0xffff0000, v109
	v_cvt_pk_bf16_f32 v4, v4, v5
	s_and_b64 vcc, exec, s[40:41]
	v_add_f32_e32 v13, 1.0, v13
	v_rcp_f32_e32 v16, v13
	v_mul_f32_e32 v13, 0xbfb8aa3b, v15
	v_exp_f32_e32 v13, v13
	s_nop 0
	v_add_f32_e32 v13, 1.0, v13
	v_rcp_f32_e32 v17, v13
	s_nop 0
	v_pk_mul_f32 v[14:15], v[16:17], v[14:15]
	s_nop 0
	v_pk_mul_f32 v[6:7], v[14:15], v[6:7]
	v_lshlrev_b32_e32 v14, 16, v110
	v_mul_f32_e32 v13, 0xbfb8aa3b, v14
	v_exp_f32_e32 v13, v13
	v_and_b32_e32 v15, 0xffff0000, v110
	v_cvt_pk_bf16_f32 v5, v6, v7
	v_add_f32_e32 v13, 1.0, v13
	v_rcp_f32_e32 v16, v13
	v_mul_f32_e32 v13, 0xbfb8aa3b, v15
	v_exp_f32_e32 v13, v13
	s_nop 0
	v_add_f32_e32 v13, 1.0, v13
	v_rcp_f32_e32 v17, v13
	s_nop 0
	v_pk_mul_f32 v[14:15], v[16:17], v[14:15]
	s_waitcnt lgkmcnt(0)
	v_pk_mul_f32 v[8:9], v[14:15], v[8:9]
	v_lshlrev_b32_e32 v14, 16, v111
	v_mul_f32_e32 v13, 0xbfb8aa3b, v14
	v_exp_f32_e32 v13, v13
	v_and_b32_e32 v15, 0xffff0000, v111
	v_cvt_pk_bf16_f32 v6, v8, v9
	v_add_f32_e32 v13, 1.0, v13
	v_rcp_f32_e32 v16, v13
	v_mul_f32_e32 v13, 0xbfb8aa3b, v15
	v_exp_f32_e32 v13, v13
	s_nop 0
	v_add_f32_e32 v13, 1.0, v13
	v_rcp_f32_e32 v17, v13
	v_ashrrev_i32_e32 v13, 31, v12
	v_lshlrev_b64 v[8:9], 11, v[12:13]
	v_lshl_add_u64 v[8:9], v[0:1], 0, v[8:9]
	v_pk_mul_f32 v[14:15], v[16:17], v[14:15]
	s_nop 0
	v_pk_mul_f32 v[10:11], v[14:15], v[10:11]
	v_lshlrev_b32_e32 v14, 16, v104
	v_mul_f32_e32 v13, 0xbfb8aa3b, v14
	v_exp_f32_e32 v13, v13
	v_and_b32_e32 v15, 0xffff0000, v104
	v_cvt_pk_bf16_f32 v7, v10, v11
	global_store_dwordx4 v[8:9], v[4:7], off offset:1024
	v_add_f32_e32 v13, 1.0, v13
	v_rcp_f32_e32 v16, v13
	v_mul_f32_e32 v13, 0xbfb8aa3b, v15
	v_exp_f32_e32 v13, v13
	v_add_u32_e32 v4, 64, v2
	v_ashrrev_i32_e32 v12, 3, v4
	v_lshl_add_u32 v8, v12, 8, v3
	v_add_f32_e32 v13, 1.0, v13
	v_rcp_f32_e32 v17, v13
	ds_read_b128 v[4:7], v8
	ds_read_b128 v[8:11], v8 offset:16
	v_pk_mul_f32 v[14:15], v[16:17], v[14:15]
	s_waitcnt lgkmcnt(1)
; #define LAS __attribute__((address_space(3)))
; DI unsigned pk2(float lo, float hi) { typedef float f2 __attribute__((ext_vector_type(2))); typedef __bf16 b2 __attribute__((ext_vector_type(2))); f2 v = {lo, hi}; b2 b = __builtin_convertvector(v, b2); return __builtin_bit_cast(unsigned, b); }
; DI float bf_lo(unsigned w) { return __uint_as_float(w << 16); }
; DI float bf_hi(unsigned w) { return __uint_as_float(w & 0xffff0000u); }
; DI void phase_ret_out(const Params& p, const Grp& G, int layer, LAS unsigned char* lds, int tid, int wave, int lane, bool dry) {
;     ...
;         { int lv = lane; asm volatile("" : "+v"(lv));
;           bf16_t* ob = (dry ? (bf16_t*)(p.ws + OFF_DUMMY) : mix + row0 * MIXW) + (size_t)(32 * qg) * MIXW + 512 + head * 64; const bf16_t* gb = rest + (row0 + 32 * qg) * RESTW + R_RG + head * 64;
; #pragma unroll
;           for (int i = 0; i < 4; ++i) { const int q = lv + 64 * i, row = q >> 3, ch = q & 7;
;             const f32x4 a0 = *(const LAS f32x4*)(stg + row * 64 + ch * 8), a1 = *(const LAS f32x4*)(stg + row * 64 + ch * 8 + 4);
;             const u32x4 gw = gwv[i];
;             float gv[8] = {bf_lo(gw.x), bf_hi(gw.x), bf_lo(gw.y), bf_hi(gw.y), bf_lo(gw.z), bf_hi(gw.z), bf_lo(gw.w), bf_hi(gw.w)}; float ov[8];
; #pragma unroll
;             for (int e = 0; e < 8; ++e) ov[e] = (e < 4 ? a0[e & 3] : a1[e & 3]) * (gv[e] * __builtin_amdgcn_rcpf(1.f + __expf(-gv[e])));
;             u32x4 w; w.x = pk2(ov[0], ov[1]); w.y = pk2(ov[2], ov[3]); w.z = pk2(ov[4], ov[5]); w.w = pk2(ov[6], ov[7]);
;             *(u32x4*)(ob + (size_t)row * MIXW + ch * 8) = w; } }
	v_pk_mul_f32 v[4:5], v[14:15], v[4:5]
	v_lshlrev_b32_e32 v14, 16, v105
	v_mul_f32_e32 v13, 0xbfb8aa3b, v14
	v_exp_f32_e32 v13, v13
	v_and_b32_e32 v15, 0xffff0000, v105
	v_cvt_pk_bf16_f32 v4, v4, v5
	v_add_f32_e32 v13, 1.0, v13
	v_rcp_f32_e32 v16, v13
	v_mul_f32_e32 v13, 0xbfb8aa3b, v15
	v_exp_f32_e32 v13, v13
	s_nop 0
	v_add_f32_e32 v13, 1.0, v13
	v_rcp_f32_e32 v17, v13
	s_nop 0
	v_pk_mul_f32 v[14:15], v[16:17], v[14:15]
	s_nop 0
	v_pk_mul_f32 v[6:7], v[14:15], v[6:7]
	v_lshlrev_b32_e32 v14, 16, v106
	v_mul_f32_e32 v13, 0xbfb8aa3b, v14
	v_exp_f32_e32 v13, v13
	v_and_b32_e32 v15, 0xffff0000, v106
	v_cvt_pk_bf16_f32 v5, v6, v7
	v_add_f32_e32 v13, 1.0, v13
	v_rcp_f32_e32 v16, v13
	v_mul_f32_e32 v13, 0xbfb8aa3b, v15
	v_exp_f32_e32 v13, v13
	s_nop 0
	v_add_f32_e32 v13, 1.0, v13
	v_rcp_f32_e32 v17, v13
	s_nop 0
	v_pk_mul_f32 v[14:15], v[16:17], v[14:15]
	s_waitcnt lgkmcnt(0)
	v_pk_mul_f32 v[8:9], v[14:15], v[8:9]
	v_lshlrev_b32_e32 v14, 16, v107
	v_mul_f32_e32 v13, 0xbfb8aa3b, v14
	v_exp_f32_e32 v13, v13
	v_and_b32_e32 v15, 0xffff0000, v107
	v_cvt_pk_bf16_f32 v6, v8, v9
	v_add_f32_e32 v13, 1.0, v13
	v_rcp_f32_e32 v16, v13
	v_mul_f32_e32 v13, 0xbfb8aa3b, v15
	v_exp_f32_e32 v13, v13
	s_nop 0
	v_add_f32_e32 v13, 1.0, v13
	v_rcp_f32_e32 v17, v13
	v_ashrrev_i32_e32 v13, 31, v12
	v_lshlrev_b64 v[8:9], 11, v[12:13]
	v_lshl_add_u64 v[8:9], v[0:1], 0, v[8:9]
	v_pk_mul_f32 v[14:15], v[16:17], v[14:15]
	s_nop 0
	v_pk_mul_f32 v[10:11], v[14:15], v[10:11]
	v_lshlrev_b32_e32 v14, 16, v100
	v_mul_f32_e32 v13, 0xbfb8aa3b, v14
	v_exp_f32_e32 v13, v13
	v_and_b32_e32 v15, 0xffff0000, v100
	v_cvt_pk_bf16_f32 v7, v10, v11
	global_store_dwordx4 v[8:9], v[4:7], off offset:1024
	v_add_f32_e32 v13, 1.0, v13
	v_rcp_f32_e32 v16, v13
	v_mul_f32_e32 v13, 0xbfb8aa3b, v15
	v_exp_f32_e32 v13, v13
	v_add_u32_e32 v4, 0x80, v2
	v_ashrrev_i32_e32 v12, 3, v4
	v_lshl_add_u32 v8, v12, 8, v3
	v_add_f32_e32 v13, 1.0, v13
	v_rcp_f32_e32 v17, v13
	ds_read_b128 v[4:7], v8
	ds_read_b128 v[8:11], v8 offset:16
	v_add_u32_e32 v2, 0xc0, v2
	v_pk_mul_f32 v[14:15], v[16:17], v[14:15]
	s_waitcnt lgkmcnt(1)
	v_pk_mul_f32 v[4:5], v[14:15], v[4:5]
	v_lshlrev_b32_e32 v14, 16, v101
	v_mul_f32_e32 v13, 0xbfb8aa3b, v14
	v_exp_f32_e32 v13, v13
	v_and_b32_e32 v15, 0xffff0000, v101
	v_cvt_pk_bf16_f32 v4, v4, v5
	v_add_f32_e32 v13, 1.0, v13
	v_rcp_f32_e32 v16, v13
	v_mul_f32_e32 v13, 0xbfb8aa3b, v15
	v_exp_f32_e32 v13, v13
	s_nop 0
	v_add_f32_e32 v13, 1.0, v13
	v_rcp_f32_e32 v17, v13
	s_nop 0
	v_pk_mul_f32 v[14:15], v[16:17], v[14:15]
	s_nop 0
	v_pk_mul_f32 v[6:7], v[14:15], v[6:7]
	v_lshlrev_b32_e32 v14, 16, v102
	v_mul_f32_e32 v13, 0xbfb8aa3b, v14
	v_exp_f32_e32 v13, v13
	v_and_b32_e32 v15, 0xffff0000, v102
	v_cvt_pk_bf16_f32 v5, v6, v7
	v_add_f32_e32 v13, 1.0, v13
	v_rcp_f32_e32 v16, v13
	v_mul_f32_e32 v13, 0xbfb8aa3b, v15
	v_exp_f32_e32 v13, v13
	s_nop 0
	v_add_f32_e32 v13, 1.0, v13
	v_rcp_f32_e32 v17, v13
	s_nop 0
	v_pk_mul_f32 v[14:15], v[16:17], v[14:15]
	s_waitcnt lgkmcnt(0)
	v_pk_mul_f32 v[8:9], v[14:15], v[8:9]
	v_lshlrev_b32_e32 v14, 16, v103
	v_mul_f32_e32 v13, 0xbfb8aa3b, v14
	v_exp_f32_e32 v13, v13
	v_and_b32_e32 v15, 0xffff0000, v103
	v_cvt_pk_bf16_f32 v6, v8, v9
	v_add_f32_e32 v13, 1.0, v13
	v_rcp_f32_e32 v16, v13
	v_mul_f32_e32 v13, 0xbfb8aa3b, v15
	v_exp_f32_e32 v13, v13
	s_nop 0
	v_add_f32_e32 v13, 1.0, v13
	v_rcp_f32_e32 v17, v13
	v_ashrrev_i32_e32 v13, 31, v12
	v_lshlrev_b64 v[8:9], 11, v[12:13]
	v_lshlrev_b32_e32 v12, 16, v96
	v_pk_mul_f32 v[14:15], v[16:17], v[14:15]
	v_and_b32_e32 v13, 0xffff0000, v96
	v_pk_mul_f32 v[10:11], v[14:15], v[10:11]
	v_lshl_add_u64 v[8:9], v[0:1], 0, v[8:9]
	v_cvt_pk_bf16_f32 v7, v10, v11
	v_mul_f32_e32 v11, 0xbfb8aa3b, v12
	v_exp_f32_e32 v11, v11
	v_ashrrev_i32_e32 v10, 3, v2
	global_store_dwordx4 v[8:9], v[4:7], off offset:1024
	v_add_f32_e32 v11, 1.0, v11
	v_rcp_f32_e32 v14, v11
	v_mul_f32_e32 v11, 0xbfb8aa3b, v13
	v_exp_f32_e32 v11, v11
	v_lshl_add_u32 v6, v10, 8, v3
	ds_read_b128 v[2:5], v6
	ds_read_b128 v[6:9], v6 offset:16
	v_add_f32_e32 v11, 1.0, v11
	v_rcp_f32_e32 v15, v11
	s_nop 0
	v_pk_mul_f32 v[12:13], v[14:15], v[12:13]
	s_waitcnt lgkmcnt(1)
	v_pk_mul_f32 v[2:3], v[12:13], v[2:3]
	v_lshlrev_b32_e32 v12, 16, v97
	v_mul_f32_e32 v11, 0xbfb8aa3b, v12
	v_exp_f32_e32 v11, v11
	v_and_b32_e32 v13, 0xffff0000, v97
	v_cvt_pk_bf16_f32 v2, v2, v3
	v_add_f32_e32 v11, 1.0, v11
	v_rcp_f32_e32 v14, v11
	v_mul_f32_e32 v11, 0xbfb8aa3b, v13
	v_exp_f32_e32 v11, v11
	s_nop 0
	v_add_f32_e32 v11, 1.0, v11
	v_rcp_f32_e32 v15, v11
	s_nop 0
	v_pk_mul_f32 v[12:13], v[14:15], v[12:13]
	s_nop 0
	v_pk_mul_f32 v[4:5], v[12:13], v[4:5]
	v_lshlrev_b32_e32 v12, 16, v98
	v_mul_f32_e32 v11, 0xbfb8aa3b, v12
	v_exp_f32_e32 v11, v11
	v_and_b32_e32 v13, 0xffff0000, v98
	v_cvt_pk_bf16_f32 v3, v4, v5
	v_add_f32_e32 v11, 1.0, v11
	v_rcp_f32_e32 v14, v11
	v_mul_f32_e32 v11, 0xbfb8aa3b, v13
	v_exp_f32_e32 v11, v11
	s_nop 0
	v_add_f32_e32 v11, 1.0, v11
	v_rcp_f32_e32 v15, v11
	s_nop 0
	v_pk_mul_f32 v[12:13], v[14:15], v[12:13]
	s_waitcnt lgkmcnt(0)
	v_pk_mul_f32 v[6:7], v[12:13], v[6:7]
	v_lshlrev_b32_e32 v12, 16, v99
	v_mul_f32_e32 v11, 0xbfb8aa3b, v12
	v_exp_f32_e32 v11, v11
	v_and_b32_e32 v13, 0xffff0000, v99
	v_cvt_pk_bf16_f32 v4, v6, v7
	v_add_f32_e32 v11, 1.0, v11
	v_rcp_f32_e32 v14, v11
	v_mul_f32_e32 v11, 0xbfb8aa3b, v13
	v_exp_f32_e32 v11, v11
	s_nop 0
	v_add_f32_e32 v11, 1.0, v11
	v_rcp_f32_e32 v15, v11
	v_ashrrev_i32_e32 v11, 31, v10
	v_lshlrev_b64 v[6:7], 11, v[10:11]
	v_lshl_add_u64 v[0:1], v[0:1], 0, v[6:7]
	v_pk_mul_f32 v[12:13], v[14:15], v[12:13]
	s_nop 0
	v_pk_mul_f32 v[8:9], v[12:13], v[8:9]
	s_nop 0
	v_cvt_pk_bf16_f32 v5, v8, v9
	global_store_dwordx4 v[0:1], v[2:5], off offset:1024
	s_cbranch_vccz .LBB0_419
